# grid barrier: XCD leaders no longer bump the (now unused) per-XCD release generation, so they do not wait for that atomic before the closing barrier
# baseline (speedup 1.0000x reference)
.LBB0_714:
	s_or_b64 exec, exec, s[0:1]
	s_mov_b64 s[0:1], exec
	v_mbcnt_lo_u32_b32 v0, s0, 0
	v_mbcnt_hi_u32_b32 v0, s1, v0
	v_cmp_eq_u32_e32 vcc, 0, v0
	s_waitcnt vmcnt(0)
	buffer_inv sc1
	s_and_saveexec_b64 s[4:5], vcc
	s_cbranch_execz .LBB0_20
	s_bcnt1_i32_b64 s0, s[0:1]
	v_mov_b32_e32 v0, s0
	v_readlane_b32 s0, v254, 9
	v_readlane_b32 s1, v254, 10
	s_nop 4
	s_branch .LBB0_20
